# first grid seam: cooperative-groups sync replaced by single-use flat counter barrier (release/arrive/spin/acquire)
# baseline (speedup 1.0000x reference)
.LBB0_123:
	s_or_b64 exec, exec, s[4:5]
	s_cmp_lt_i32 s69, 2
	s_cbranch_scc1 .LBB0_135
	s_waitcnt vmcnt(0) lgkmcnt(0)
	s_barrier
	s_and_saveexec_b64 s[4:5], s[10:11]
	s_cbranch_execz .Lgs_join
	buffer_wbl2 sc1
	s_waitcnt vmcnt(0)
	v_mov_b32_e32 v1, 0
	v_mov_b32_e32 v2, 1
	global_atomic_add v1, v2, s[34:35] offset:256
	s_load_dword s6, s[0:1], 0xb8
	s_waitcnt lgkmcnt(0)
.Lgs_spin:
	global_load_dword v3, v1, s[34:35] offset:256 sc1
	s_waitcnt vmcnt(0)
	v_readfirstlane_b32 s7, v3
	s_cmp_lt_u32 s7, s6
	s_cbranch_scc0 .Lgs_done
	s_sleep 1
	s_branch .Lgs_spin
.Lgs_done:
	buffer_inv sc1
	s_waitcnt vmcnt(0)
